# v48 + retention chunk updates done only by the prompt-attention workgroups (2 items each); sample-attention workgroups start streaming at once
# baseline (speedup 1.0000x reference)
; #define LAS __attribute__((address_space(3)))
; __device__ __forceinline__ unsigned cvtpk(float lo, float hi) { f32x2_t v = {lo, hi}; bf16x2_t b = __builtin_convertvector(v, bf16x2_t); return __builtin_bit_cast(unsigned, b); }
; __device__ __forceinline__ void ret_upd_phase(LAS unsigned char* lds, const bf16* __restrict__ QKVb, float* __restrict__ UPD, unsigned* cnt, int tid, int wave, int lane) {
;     constexpr int RSV = 272, RSK = 144, GRP = 128 * RSV + 128 * RSK;
;     const int grp = wave >> 2, dt = wave & 3;
;     LAS unsigned char* vb = lds + grp * GRP;
;     LAS unsigned char* kb = vb + 128 * RSV;
;     const int i = lane & 31, hh = lane >> 5, i16 = lane & 15, tq = i16 >> 2, tp = i16 & 3, blk = (lane >> 4) & 1;
;     for (int it = blockIdx.x; it < 256; it += gridDim.x) {
;         const int item = it * 2 + grp, n = item >> 2, h = item & 3;
;         const float lg2 = log_g(h) * 1.4426950408889634f;
;         const int t4 = tid & 255;
; #pragma unroll
;         for (int c = 0; c < 8; ++c) { const int e = t4 + 256 * c, rowk = e >> 4, ch = e & 15;
;             *(LAS v4u*)(vb + rowk * RSV + 16 * ch) = *(const v4u*)(QKVb + (size_t)(n * 128 + rowk) * INW + C_VR + h * 128 + 8 * ch); }
; #pragma unroll
;         for (int c = 0; c < 4; ++c) { const int e = t4 + 256 * c, rowk = e >> 3, ch = e & 7;
;             const v4u x = *(const v4u*)(QKVb + (size_t)(n * 128 + rowk) * INW + C_KR + h * 64 + 8 * ch);
;             const float w = __builtin_amdgcn_exp2f((float)(127 - rowk) * lg2);
;             v4u y; y.x = cvtpk(bf_lo(x.x) * w, bf_hi(x.x) * w); y.y = cvtpk(bf_lo(x.y) * w, bf_hi(x.y) * w); y.z = cvtpk(bf_lo(x.z) * w, bf_hi(x.z) * w); y.w = cvtpk(bf_lo(x.w) * w, bf_hi(x.w) * w);
;             *(LAS v4u*)(kb + rowk * RSK + 16 * ch) = y; }
;         __syncthreads();
;         f32x16 a0, a1;
; #pragma unroll
;         for (int e = 0; e < 16; ++e) { a0[e] = 0.f; a1[e] = 0.f; }
; #pragma unroll
;         for (int ks = 0; ks < 8; ++ks) {
;             const LAS unsigned char* va = vb + (16 * ks + 8 * hh + tq) * RSV + (32 * dt + 16 * blk + 4 * tp) * 2;
;             const LAS unsigned char* ka = kb + (16 * ks + 8 * hh + tq) * RSK + (16 * blk + 4 * tp) * 2;
;             const s16x4 vlo = vtr(va), vhi = vtr(va + 4 * RSV), k0lo = vtr(ka), k0hi = vtr(ka + 4 * RSK), k1lo = vtr(ka + 64), k1hi = vtr(ka + 4 * RSK + 64);
.LBB0_949:
	s_or_b64 exec, exec, s[0:1]
	s_add_u32 s36, s90, 0x21700000
	s_addc_u32 s37, s91, 0
	s_mov_b64 s[24:25], 0
	s_nop 0
	s_and_b64 vcc, exec, s[24:25]
	s_waitcnt lgkmcnt(0)
	s_barrier
	s_cbranch_vccnz .LBB0_961
	s_and_b64 vcc, exec, s[52:53]
	s_cbranch_vccnz .LBB0_961
	s_cmpk_ge_i32 s86, 128
	s_cbranch_scc1 .LBB0_961
	s_add_u32 s0, s90, 0x10000
	v_readlane_b32 s5, v254, 0
	s_addc_u32 s1, s91, 0
	s_lshr_b32 s2, s5, 8
	v_bfe_u32 v4, v0, 2, 2
	v_lshrrev_b32_e32 v6, 5, v162
	s_bfe_u32 s5, s5, 0x20006
	v_and_b32_e32 v3, 16, v0
	s_mul_i32 s4, s2, 0xd000
	v_lshl_or_b32 v9, v6, 3, v4
	s_lshl_b32 s6, s5, 5
	v_and_b32_e32 v4, 12, v163
	s_add_i32 s4, s4, 0
	v_or3_b32 v10, s6, v3, v4
	v_or_b32_e32 v3, v4, v3
	v_lshl_add_u32 v7, v167, 4, s4
	v_lshl_add_u32 v8, v1, 4, s4
	v_lshl_add_u32 v10, v10, 1, s4
	v_lshl_add_u32 v3, v3, 1, s4
	s_lshl_b32 s4, s5, 13
	v_and_b32_e32 v5, 31, v0
	s_add_u32 s4, s36, s4
	s_waitcnt vmcnt(2)
	v_mov_b32_e32 v35, 0
	s_addc_u32 s5, s37, 0
	v_lshlrev_b32_e32 v34, 2, v5
	v_lshl_add_u64 v[4:5], s[4:5], 0, v[34:35]
	s_movk_i32 s4, 0x100
	v_or_b32_sdwa v12, v0, s4 dst_sel:DWORD dst_unused:UNUSED_PAD src0_sel:BYTE_0 src1_sel:DWORD
	s_movk_i32 s4, 0x200
	v_or_b32_sdwa v14, v0, s4 dst_sel:DWORD dst_unused:UNUSED_PAD src0_sel:BYTE_0 src1_sel:DWORD
	v_or_b32_e32 v16, 0x300, v0
	v_bfe_u32 v50, v0, 3, 5
	v_lshrrev_b32_e32 v52, 3, v12
	v_lshrrev_b32_e32 v54, 3, v14
	v_lshrrev_b32_e32 v56, 3, v16
	v_bfe_u32 v42, v0, 4, 4
	v_lshrrev_b32_e32 v43, 4, v12
	v_lshrrev_b32_e32 v44, 4, v14
	v_lshrrev_b32_e32 v45, 4, v16
	v_or_b32_e32 v49, 0x70, v186
	v_xor_b32_e32 v19, 0x7f, v50
	v_xor_b32_e32 v12, 0x7f, v52
	v_xor_b32_e32 v14, 0x7f, v54
	v_xor_b32_e32 v16, 0x7f, v56
	s_lshl_b32 s4, s86, 1
	v_lshlrev_b32_e32 v2, 3, v1
	v_mul_u32_u24_e32 v11, 0x110, v42
	v_mul_u32_u24_e32 v13, 0x110, v43
	v_mul_u32_u24_e32 v15, 0x110, v44
	v_mul_u32_u24_e32 v17, 0x110, v45
	v_mul_u32_u24_e32 v18, 0x110, v49
	v_cvt_f32_ubyte0_e32 v51, v19
	v_mul_u32_u24_e32 v19, 0x90, v50
	v_cvt_f32_ubyte0_e32 v53, v12
	v_mul_u32_u24_e32 v12, 0x90, v52
	v_cvt_f32_ubyte0_e32 v55, v14
	v_mul_u32_u24_e32 v14, 0x90, v54
	v_cvt_f32_ubyte0_e32 v57, v16
	v_mul_u32_u24_e32 v16, 0x90, v56
	v_mul_u32_u24_e32 v20, 0x110, v9
	v_mul_u32_u24_e32 v9, 0x90, v9
	v_lshlrev_b32_e32 v34, 10, v6
	s_add_i32 s4, s2, s4
	s_lshl_b32 s5, s86, 6
	s_lshl_b32 s2, s2, 5
	s_mov_b32 s3, 0
	v_or_b32_e32 v46, 64, v42
	v_or_b32_e32 v47, 0x50, v42
	v_or_b32_e32 v48, 0x60, v42
	v_lshl_add_u64 v[36:37], v[4:5], 0, v[34:35]
	s_movk_i32 s10, 0x100
	s_add_i32 s11, s5, s2
	s_movk_i32 s12, 0x2000
	s_movk_i32 s13, 0x1800
	v_mov_b64_e32 v[38:39], s[72:73]
	v_lshlrev_b32_e32 v34, 1, v134
	s_movk_i32 s14, 0x1000
	v_add_u32_e32 v58, v7, v11
	v_add_u32_e32 v59, v7, v13
	v_add_u32_e32 v60, v7, v15
	v_add_u32_e32 v61, v7, v17
	v_add_u32_e32 v62, v7, v18
	v_lshlrev_b32_e32 v40, 1, v2
	v_mov_b32_e32 v41, v35
	v_add_u32_e32 v63, v8, v19
	v_add_u32_e32 v64, v8, v12
	v_add_u32_e32 v65, v8, v14
	v_add_u32_e32 v66, v8, v16
	v_add_u32_e32 v67, v10, v20
	v_add_u32_e32 v68, v3, v9
	v_mov_b32_e32 v69, 0xbbb906ce
	v_mov_b32_e32 v70, 0xbc3963dd
	s_mov_b32 s15, s86
	s_branch .LBB0_953
.LBB0_952:
	s_or_b64 exec, exec, s[6:7]
	s_addk_i32 s15, 0x80
	s_add_i32 s4, s4, s10
	s_add_i32 s11, s11, s12
	s_cmpk_lt_i32 s15, 0x100
	s_cbranch_scc0 .LBB0_961
